# nt also on the final output stores
# speedup vs baseline: 1.0227x; 1.0037x over previous
; __device__ __forceinline__ unsigned pk2(float lo, float hi) { return f2bf(lo) | (f2bf(hi) << 16); }
; template <bool OUT_BF16>
; __device__ __forceinline__ void rmsnorm_rows(Frame& F, const float* X, const float* gain, void* O) {
;     ...
;     for (int m = gw; m < S; m += NGW) {
;         const f32x4* xr = (const f32x4*)(X + (size_t)m * DM) + F.lane;
;         f32x4 v[8]; float s = 0.f;
; #pragma unroll
;         for (int j = 0; j < 8; ++j) { v[j] = xr[64 * j]; s += (v[j].x * v[j].x + v[j].y * v[j].y) + (v[j].z * v[j].z + v[j].w * v[j].w); }
;         const float rs = 1.f / sqrtf(wave_sum(s) * (1.f / DM) + NORM_EPS);
;         if (OUT_BF16) {
;             u32x2* o8 = (u32x2*)((bf16_t*)O + (size_t)m * DM) + F.lane;
; #pragma unroll
;             for (int j = 0; j < 8; ++j) { u32x2 w; w.x = pk2(v[j].x * rs * gv[j].x, v[j].y * rs * gv[j].y); w.y = pk2(v[j].z * rs * gv[j].z, v[j].w * rs * gv[j].w); o8[64 * j] = w; }
;         } else {
;             f32x4* o = (f32x4*)((float*)O + (size_t)m * DM) + F.lane;
; #pragma unroll
;             for (int j = 0; j < 8; ++j) o[64 * j] = v[j] * rs * gv[j];
;         }
.LBB0_1603:
	global_load_dwordx4 v[38:41], v[32:33], off offset:-4096 nt
	global_load_dwordx4 v[42:45], v[32:33], off offset:-3072 nt
	global_load_dwordx4 v[46:49], v[32:33], off offset:-2048 nt
	global_load_dwordx4 v[50:53], v[32:33], off offset:-1024 nt
	global_load_dwordx4 v[54:57], v[32:33], off nt
	global_load_dwordx4 v[58:61], v[32:33], off offset:1024 nt
	global_load_dwordx4 v[62:65], v[32:33], off offset:2048 nt
	global_load_dwordx4 v[66:69], v[32:33], off offset:3072 nt
	v_mov_b32_e32 v37, 0
	v_mov_b32_e32 v70, 0
	s_add_i32 s2, s2, s4
	s_cmpk_lt_i32 s2, 0x4000
	s_waitcnt vmcnt(7)
	v_mul_f32_e32 v71, v39, v39
	v_mul_f32_e32 v72, v41, v41
	s_waitcnt vmcnt(6)
	v_mul_f32_e32 v73, v43, v43
	v_mul_f32_e32 v74, v45, v45
	s_waitcnt vmcnt(5)
	v_mul_f32_e32 v75, v47, v47
	v_mul_f32_e32 v76, v49, v49
	v_fmac_f32_e32 v71, v38, v38
	v_fmac_f32_e32 v72, v40, v40
	v_fmac_f32_e32 v73, v42, v42
	v_fmac_f32_e32 v74, v44, v44
	s_waitcnt vmcnt(4)
	v_mul_f32_e32 v77, v51, v51
	v_mul_f32_e32 v78, v53, v53
	v_fmac_f32_e32 v75, v46, v46
	v_fmac_f32_e32 v76, v48, v48
	v_add_f32_e32 v71, v71, v72
	v_add_f32_e32 v72, v73, v74
	s_waitcnt vmcnt(3)
	v_mul_f32_e32 v79, v55, v55
	v_mul_f32_e32 v80, v57, v57
	v_fmac_f32_e32 v77, v50, v50
	v_fmac_f32_e32 v78, v52, v52
	v_add_f32_e32 v73, v75, v76
	v_add_f32_e32 v71, v71, v72
	s_waitcnt vmcnt(2)
	v_mul_f32_e32 v81, v59, v59
	v_mul_f32_e32 v82, v61, v61
	v_fmac_f32_e32 v79, v54, v54
	v_fmac_f32_e32 v80, v56, v56
	v_add_f32_e32 v74, v77, v78
	v_add_f32_e32 v71, v71, v73
	s_waitcnt vmcnt(1)
	v_mul_f32_e32 v83, v63, v63
	v_mul_f32_e32 v84, v65, v65
	v_fmac_f32_e32 v81, v58, v58
	v_fmac_f32_e32 v82, v60, v60
	v_add_f32_e32 v75, v79, v80
	v_add_f32_e32 v71, v71, v74
	s_waitcnt vmcnt(0)
	v_mul_f32_e32 v85, v67, v67
	v_mul_f32_e32 v86, v69, v69
	v_fmac_f32_e32 v83, v62, v62
	v_fmac_f32_e32 v84, v64, v64
	v_add_f32_e32 v76, v81, v82
	v_add_f32_e32 v71, v71, v75
	v_fmac_f32_e32 v85, v66, v66
	v_fmac_f32_e32 v86, v68, v68
	v_add_f32_e32 v77, v83, v84
	v_add_f32_e32 v71, v71, v76
	v_add_f32_e32 v78, v85, v86
	v_add_f32_e32 v71, v71, v77
	v_add_f32_e32 v71, v71, v78
	s_nop 1
	v_add_f32_dpp v71, v71, v71 quad_perm:[1,0,3,2] row_mask:0xf bank_mask:0xf bound_ctrl:1
	s_nop 1
	v_add_f32_dpp v71, v71, v71 quad_perm:[2,3,0,1] row_mask:0xf bank_mask:0xf bound_ctrl:1
	s_nop 1
	v_add_f32_dpp v71, v71, v71 row_half_mirror row_mask:0xf bank_mask:0xf bound_ctrl:1
	s_nop 1
	v_add_f32_dpp v71, v71, v71 row_mirror row_mask:0xf bank_mask:0xf bound_ctrl:1
	s_nop 1
	v_mov_b32_dpp v37, v71 row_bcast:15 row_mask:0xa bank_mask:0xf
	v_add_f32_e32 v37, v71, v37
	s_nop 1
	v_mov_b32_dpp v70, v37 row_bcast:31 row_mask:0xc bank_mask:0xf
	v_add_f32_e32 v37, v37, v70
	s_nop 0
	v_readlane_b32 s0, v37, 63
	s_nop 1
	v_fma_f32 v37, s0, v35, v34
	v_mul_f32_e32 v70, 0x4f800000, v37
	v_cmp_gt_f32_e32 vcc, s3, v37
	s_nop 1
	v_cndmask_b32_e32 v37, v37, v70, vcc
	v_sqrt_f32_e32 v70, v37
	s_nop 0
	v_add_u32_e32 v71, -1, v70
	v_add_u32_e32 v72, 1, v70
	v_fma_f32 v73, -v71, v70, v37
	v_fma_f32 v74, -v72, v70, v37
	v_cmp_ge_f32_e64 s[0:1], 0, v73
	s_nop 1
	v_cndmask_b32_e64 v70, v70, v71, s[0:1]
	v_cmp_lt_f32_e64 s[0:1], 0, v74
	s_nop 1
	v_cndmask_b32_e64 v70, v70, v72, s[0:1]
	v_mul_f32_e32 v71, 0x37800000, v70
	v_cndmask_b32_e32 v70, v70, v71, vcc
	v_cmp_class_f32_e32 vcc, v37, v36
	s_nop 1
	v_cndmask_b32_e32 v37, v70, v37, vcc
	v_div_scale_f32 v70, s[0:1], v37, v37, 1.0
	v_rcp_f32_e32 v71, v70
	v_div_scale_f32 v72, vcc, 1.0, v37, 1.0
	v_fma_f32 v73, -v70, v71, 1.0
	v_fmac_f32_e32 v71, v73, v71
	v_mul_f32_e32 v73, v72, v71
	v_fma_f32 v74, -v70, v73, v72
	v_fmac_f32_e32 v73, v74, v71
	v_fma_f32 v70, -v70, v73, v72
	v_div_fmas_f32 v70, v70, v71, v73
	v_div_fixup_f32 v70, v70, v37, 1.0
	v_pk_mul_f32 v[38:39], v[38:39], v[70:71] op_sel_hi:[1,0]
	v_pk_mul_f32 v[40:41], v[40:41], v[70:71] op_sel_hi:[1,0]
	v_pk_mul_f32 v[42:43], v[42:43], v[70:71] op_sel_hi:[1,0]
	v_pk_mul_f32 v[44:45], v[44:45], v[70:71] op_sel_hi:[1,0]
	v_pk_mul_f32 v[46:47], v[46:47], v[70:71] op_sel_hi:[1,0]
	v_pk_mul_f32 v[48:49], v[48:49], v[70:71] op_sel_hi:[1,0]
	v_pk_mul_f32 v[50:51], v[50:51], v[70:71] op_sel_hi:[1,0]
	v_pk_mul_f32 v[52:53], v[52:53], v[70:71] op_sel_hi:[1,0]
	v_pk_mul_f32 v[54:55], v[54:55], v[70:71] op_sel_hi:[1,0]
	v_pk_mul_f32 v[56:57], v[56:57], v[70:71] op_sel_hi:[1,0]
	v_pk_mul_f32 v[58:59], v[58:59], v[70:71] op_sel_hi:[1,0]
	v_pk_mul_f32 v[60:61], v[60:61], v[70:71] op_sel_hi:[1,0]
	v_pk_mul_f32 v[62:63], v[62:63], v[70:71] op_sel_hi:[1,0]
	v_pk_mul_f32 v[64:65], v[64:65], v[70:71] op_sel_hi:[1,0]
	v_pk_mul_f32 v[40:41], v[2:3], v[40:41]
	v_pk_mul_f32 v[38:39], v[0:1], v[38:39]
	v_pk_mul_f32 v[44:45], v[6:7], v[44:45]
	v_pk_mul_f32 v[42:43], v[4:5], v[42:43]
	v_pk_mul_f32 v[48:49], v[10:11], v[48:49]
	v_pk_mul_f32 v[46:47], v[8:9], v[46:47]
	v_pk_mul_f32 v[52:53], v[14:15], v[52:53]
	v_pk_mul_f32 v[50:51], v[12:13], v[50:51]
	v_pk_mul_f32 v[56:57], v[18:19], v[56:57]
	v_pk_mul_f32 v[54:55], v[16:17], v[54:55]
	v_pk_mul_f32 v[60:61], v[22:23], v[60:61]
	v_pk_mul_f32 v[58:59], v[20:21], v[58:59]
	global_store_dwordx4 v[32:33], v[38:41], off offset:-4096 nt
	global_store_dwordx4 v[32:33], v[42:45], off offset:-3072 nt
	global_store_dwordx4 v[32:33], v[46:49], off offset:-2048 nt
	global_store_dwordx4 v[32:33], v[50:53], off offset:-1024 nt
	global_store_dwordx4 v[32:33], v[54:57], off nt
	global_store_dwordx4 v[32:33], v[58:61], off offset:1024 nt
	v_pk_mul_f32 v[40:41], v[26:27], v[64:65]
	v_pk_mul_f32 v[38:39], v[24:25], v[62:63]
	global_store_dwordx4 v[32:33], v[38:41], off offset:2048 nt
	s_nop 1
	v_pk_mul_f32 v[38:39], v[66:67], v[70:71] op_sel_hi:[1,0]
	v_pk_mul_f32 v[40:41], v[68:69], v[70:71] op_sel_hi:[1,0]
	v_pk_mul_f32 v[38:39], v[28:29], v[38:39]
	v_pk_mul_f32 v[40:41], v[30:31], v[40:41]
	global_store_dwordx4 v[32:33], v[38:41], off offset:3072 nt
	v_lshl_add_u64 v[32:33], v[32:33], 0, s[6:7]
	s_cbranch_scc1 .LBB0_1603
